# blocked H + P5 residual loads without nt (keep lines in L2 for the partner wave)
# speedup vs baseline: 1.0017x; 1.0017x over previous
;     __device__ __forceinline__ void operator()(const f32x4 (&acc)[2][2][4][2], const Unit& u, int wr, int wc, int fr, int fq) const {
;     ...
;             for (int m = 0; m < 4; ++m) { const int r = u.pm * BM + ai * HALF + wr * 64 + m * 16 + fr; const size_t off = (size_t)r * 1024 + col0;
; #pragma unroll
;                 for (int bj = 0; bj < 2; ++bj) { const u32x4 w = __builtin_nontemporal_load((const u32x4*)(xb + off + bj * HALF));
;                     const f32x4 b0 = {__builtin_bit_cast(float, w.x << 16), __builtin_bit_cast(float, w.x & 0xffff0000u), __builtin_bit_cast(float, w.y << 16), __builtin_bit_cast(float, w.y & 0xffff0000u)};
;                     const f32x4 b1 = {__builtin_bit_cast(float, w.z << 16), __builtin_bit_cast(float, w.z & 0xffff0000u), __builtin_bit_cast(float, w.w << 16), __builtin_bit_cast(float, w.w & 0xffff0000u)};
;                     __builtin_nontemporal_store(b0 + acc[ai][bj][m][0], (f32x4*)(out + off + bj * HALF)); __builtin_nontemporal_store(b1 + acc[ai][bj][m][1], (f32x4*)(out + off + bj * HALF + 4)); } }
.LBB0_1501:
	v_lshl_add_u32 v144, s20, 8, v146
	v_lshl_or_b32 v142, s18, 8, v147
	v_ashrrev_i32_e32 v145, 31, v144
	v_ashrrev_i32_e32 v143, 31, v142
	v_lshlrev_b64 v[154:155], 10, v[144:145]
	v_lshl_add_u64 v[158:159], v[154:155], 0, v[142:143]
	v_lshl_add_u64 v[160:161], v[158:159], 1, s[66:67]
	global_load_dwordx4 v[154:157], v[160:161], off
	v_lshl_add_u64 v[158:159], v[158:159], 2, s[60:61]
	s_andn2_b64 vcc, exec, s[14:15]
	s_mov_b64 s[14:15], -1
	s_waitcnt vmcnt(0)
	v_lshlrev_b32_e32 v162, 16, v154
	v_and_b32_e32 v163, 0xffff0000, v154
	v_lshlrev_b32_e32 v154, 16, v155
	v_and_b32_e32 v155, 0xffff0000, v155
	v_lshlrev_b32_e32 v164, 16, v156
	v_and_b32_e32 v165, 0xffff0000, v156
	v_lshlrev_b32_e32 v156, 16, v157
	v_and_b32_e32 v157, 0xffff0000, v157
	v_pk_add_f32 v[126:127], v[126:127], v[154:155]
	v_pk_add_f32 v[124:125], v[124:125], v[162:163]
	v_pk_add_f32 v[122:123], v[122:123], v[156:157]
	v_pk_add_f32 v[120:121], v[120:121], v[164:165]
	global_store_dwordx4 v[158:159], v[124:127], off nt
	global_store_dwordx4 v[158:159], v[120:123], off offset:16 nt
	global_load_dwordx4 v[120:123], v[160:161], off offset:256
	v_or_b32_e32 v124, 16, v144
	v_ashrrev_i32_e32 v125, 31, v124
	v_lshlrev_b64 v[124:125], 10, v[124:125]
	v_lshl_add_u64 v[124:125], v[124:125], 0, v[142:143]
	v_lshl_add_u64 v[126:127], v[124:125], 1, s[66:67]
	s_waitcnt vmcnt(0)
	v_lshlrev_b32_e32 v154, 16, v120
	v_and_b32_e32 v155, 0xffff0000, v120
	v_lshlrev_b32_e32 v120, 16, v121
	v_and_b32_e32 v121, 0xffff0000, v121
	v_lshlrev_b32_e32 v156, 16, v122
	v_and_b32_e32 v157, 0xffff0000, v122
	v_lshlrev_b32_e32 v122, 16, v123
	v_and_b32_e32 v123, 0xffff0000, v123
	v_pk_add_f32 v[118:119], v[118:119], v[120:121]
	v_pk_add_f32 v[116:117], v[116:117], v[154:155]
	v_pk_add_f32 v[114:115], v[114:115], v[122:123]
	v_pk_add_f32 v[112:113], v[112:113], v[156:157]
	global_store_dwordx4 v[158:159], v[116:119], off offset:512 nt
	global_store_dwordx4 v[158:159], v[112:115], off offset:528 nt
	global_load_dwordx4 v[112:115], v[126:127], off
	v_lshl_add_u64 v[116:117], v[124:125], 2, s[60:61]
	s_waitcnt vmcnt(0)
	v_lshlrev_b32_e32 v118, 16, v112
	v_and_b32_e32 v119, 0xffff0000, v112
	v_lshlrev_b32_e32 v112, 16, v113
	v_and_b32_e32 v113, 0xffff0000, v113
	v_lshlrev_b32_e32 v120, 16, v114
	v_and_b32_e32 v121, 0xffff0000, v114
	v_lshlrev_b32_e32 v114, 16, v115
	v_and_b32_e32 v115, 0xffff0000, v115
	v_pk_add_f32 v[110:111], v[110:111], v[112:113]
	v_pk_add_f32 v[108:109], v[108:109], v[118:119]
	v_pk_add_f32 v[106:107], v[106:107], v[114:115]
	v_pk_add_f32 v[104:105], v[104:105], v[120:121]
	global_store_dwordx4 v[116:117], v[108:111], off nt
	global_store_dwordx4 v[116:117], v[104:107], off offset:16 nt
	global_load_dwordx4 v[104:107], v[126:127], off offset:256
	v_or_b32_e32 v108, 32, v144
	v_ashrrev_i32_e32 v109, 31, v108
	v_lshlrev_b64 v[108:109], 10, v[108:109]
	v_lshl_add_u64 v[108:109], v[108:109], 0, v[142:143]
	v_lshl_add_u64 v[110:111], v[108:109], 1, s[66:67]
	s_waitcnt vmcnt(0)
	v_lshlrev_b32_e32 v112, 16, v104
	v_and_b32_e32 v113, 0xffff0000, v104
	v_lshlrev_b32_e32 v104, 16, v105
	v_and_b32_e32 v105, 0xffff0000, v105
	v_lshlrev_b32_e32 v114, 16, v106
	v_and_b32_e32 v115, 0xffff0000, v106
	v_lshlrev_b32_e32 v106, 16, v107
	v_and_b32_e32 v107, 0xffff0000, v107
	v_pk_add_f32 v[102:103], v[102:103], v[104:105]
	v_pk_add_f32 v[100:101], v[100:101], v[112:113]
	v_pk_add_f32 v[98:99], v[98:99], v[106:107]
	v_pk_add_f32 v[96:97], v[96:97], v[114:115]
	global_store_dwordx4 v[116:117], v[100:103], off offset:512 nt
	global_store_dwordx4 v[116:117], v[96:99], off offset:528 nt
	global_load_dwordx4 v[96:99], v[110:111], off
	v_lshl_add_u64 v[100:101], v[108:109], 2, s[60:61]
	s_waitcnt vmcnt(0)
	v_lshlrev_b32_e32 v102, 16, v96
	v_and_b32_e32 v103, 0xffff0000, v96
	v_lshlrev_b32_e32 v96, 16, v97
	v_and_b32_e32 v97, 0xffff0000, v97
	v_lshlrev_b32_e32 v104, 16, v98
	v_and_b32_e32 v105, 0xffff0000, v98
	v_lshlrev_b32_e32 v98, 16, v99
	v_and_b32_e32 v99, 0xffff0000, v99
	v_pk_add_f32 v[94:95], v[94:95], v[96:97]
	v_pk_add_f32 v[92:93], v[92:93], v[102:103]
	v_pk_add_f32 v[90:91], v[90:91], v[98:99]
	v_pk_add_f32 v[88:89], v[88:89], v[104:105]
	global_store_dwordx4 v[100:101], v[92:95], off nt
	global_store_dwordx4 v[100:101], v[88:91], off offset:16 nt
	global_load_dwordx4 v[88:91], v[110:111], off offset:256
	v_or_b32_e32 v92, 48, v144
	v_ashrrev_i32_e32 v93, 31, v92
	v_lshlrev_b64 v[92:93], 10, v[92:93]
	v_lshl_add_u64 v[92:93], v[92:93], 0, v[142:143]
	v_lshl_add_u64 v[94:95], v[92:93], 1, s[66:67]
	s_waitcnt vmcnt(0)
	v_lshlrev_b32_e32 v96, 16, v88
	v_and_b32_e32 v97, 0xffff0000, v88
	v_lshlrev_b32_e32 v88, 16, v89
	v_and_b32_e32 v89, 0xffff0000, v89
	v_lshlrev_b32_e32 v98, 16, v90
	v_and_b32_e32 v99, 0xffff0000, v90
	v_lshlrev_b32_e32 v90, 16, v91
	v_and_b32_e32 v91, 0xffff0000, v91
	v_pk_add_f32 v[86:87], v[86:87], v[88:89]
	v_pk_add_f32 v[84:85], v[84:85], v[96:97]
	v_pk_add_f32 v[82:83], v[82:83], v[90:91]
	v_pk_add_f32 v[80:81], v[80:81], v[98:99]
	global_store_dwordx4 v[100:101], v[84:87], off offset:512 nt
	global_store_dwordx4 v[100:101], v[80:83], off offset:528 nt
	global_load_dwordx4 v[80:83], v[94:95], off
	v_lshl_add_u64 v[84:85], v[92:93], 2, s[60:61]
	s_waitcnt vmcnt(0)
;     __device__ __forceinline__ void operator()(const f32x4 (&acc)[2][2][4][2], const Unit& u, int wr, int wc, int fr, int fq) const {
;     ...
;             for (int m = 0; m < 4; ++m) { const int r = u.pm * BM + ai * HALF + wr * 64 + m * 16 + fr; const size_t off = (size_t)r * 1024 + col0;
; #pragma unroll
;                 for (int bj = 0; bj < 2; ++bj) { const u32x4 w = __builtin_nontemporal_load((const u32x4*)(xb + off + bj * HALF));
;                     const f32x4 b0 = {__builtin_bit_cast(float, w.x << 16), __builtin_bit_cast(float, w.x & 0xffff0000u), __builtin_bit_cast(float, w.y << 16), __builtin_bit_cast(float, w.y & 0xffff0000u)};
;                     const f32x4 b1 = {__builtin_bit_cast(float, w.z << 16), __builtin_bit_cast(float, w.z & 0xffff0000u), __builtin_bit_cast(float, w.w << 16), __builtin_bit_cast(float, w.w & 0xffff0000u)};
;                     __builtin_nontemporal_store(b0 + acc[ai][bj][m][0], (f32x4*)(out + off + bj * HALF)); __builtin_nontemporal_store(b1 + acc[ai][bj][m][1], (f32x4*)(out + off + bj * HALF + 4)); } }
	v_lshlrev_b32_e32 v86, 16, v80
	v_and_b32_e32 v87, 0xffff0000, v80
	v_lshlrev_b32_e32 v80, 16, v81
	v_and_b32_e32 v81, 0xffff0000, v81
	v_lshlrev_b32_e32 v88, 16, v82
	v_and_b32_e32 v89, 0xffff0000, v82
	v_lshlrev_b32_e32 v82, 16, v83
	v_and_b32_e32 v83, 0xffff0000, v83
	v_pk_add_f32 v[78:79], v[78:79], v[80:81]
	v_pk_add_f32 v[76:77], v[76:77], v[86:87]
	v_pk_add_f32 v[74:75], v[74:75], v[82:83]
	v_pk_add_f32 v[72:73], v[72:73], v[88:89]
	global_store_dwordx4 v[84:85], v[76:79], off nt
	global_store_dwordx4 v[84:85], v[72:75], off offset:16 nt
	global_load_dwordx4 v[72:75], v[94:95], off offset:256
	v_add_u32_e32 v76, 0x80, v144
	v_ashrrev_i32_e32 v77, 31, v76
	v_lshlrev_b64 v[76:77], 10, v[76:77]
	v_lshl_add_u64 v[76:77], v[76:77], 0, v[142:143]
	v_lshl_add_u64 v[78:79], v[76:77], 1, s[66:67]
	s_waitcnt vmcnt(0)
	v_lshlrev_b32_e32 v80, 16, v72
	v_and_b32_e32 v81, 0xffff0000, v72
	v_lshlrev_b32_e32 v72, 16, v73
	v_and_b32_e32 v73, 0xffff0000, v73
	v_lshlrev_b32_e32 v82, 16, v74
	v_and_b32_e32 v83, 0xffff0000, v74
	v_lshlrev_b32_e32 v74, 16, v75
	v_and_b32_e32 v75, 0xffff0000, v75
	v_pk_add_f32 v[70:71], v[70:71], v[72:73]
	v_pk_add_f32 v[68:69], v[68:69], v[80:81]
	v_pk_add_f32 v[66:67], v[66:67], v[74:75]
	v_pk_add_f32 v[64:65], v[64:65], v[82:83]
	global_store_dwordx4 v[84:85], v[68:71], off offset:512 nt
	global_store_dwordx4 v[84:85], v[64:67], off offset:528 nt
	global_load_dwordx4 v[64:67], v[78:79], off
	v_lshl_add_u64 v[68:69], v[76:77], 2, s[60:61]
	s_waitcnt vmcnt(0)
	v_lshlrev_b32_e32 v70, 16, v64
	v_and_b32_e32 v71, 0xffff0000, v64
	v_lshlrev_b32_e32 v64, 16, v65
	v_and_b32_e32 v65, 0xffff0000, v65
	v_lshlrev_b32_e32 v72, 16, v66
	v_and_b32_e32 v73, 0xffff0000, v66
	v_lshlrev_b32_e32 v66, 16, v67
	v_and_b32_e32 v67, 0xffff0000, v67
	v_pk_add_f32 v[62:63], v[62:63], v[64:65]
	v_pk_add_f32 v[60:61], v[60:61], v[70:71]
	v_pk_add_f32 v[58:59], v[58:59], v[66:67]
	v_pk_add_f32 v[56:57], v[56:57], v[72:73]
	global_store_dwordx4 v[68:69], v[60:63], off nt
	global_store_dwordx4 v[68:69], v[56:59], off offset:16 nt
	global_load_dwordx4 v[56:59], v[78:79], off offset:256
	v_add_u32_e32 v60, 0x90, v144
	v_ashrrev_i32_e32 v61, 31, v60
	v_lshlrev_b64 v[60:61], 10, v[60:61]
	v_lshl_add_u64 v[60:61], v[60:61], 0, v[142:143]
	v_lshl_add_u64 v[62:63], v[60:61], 1, s[66:67]
	s_waitcnt vmcnt(0)
	v_lshlrev_b32_e32 v64, 16, v56
	v_and_b32_e32 v65, 0xffff0000, v56
	v_lshlrev_b32_e32 v56, 16, v57
	v_and_b32_e32 v57, 0xffff0000, v57
	v_lshlrev_b32_e32 v66, 16, v58
	v_and_b32_e32 v67, 0xffff0000, v58
	v_lshlrev_b32_e32 v58, 16, v59
	v_and_b32_e32 v59, 0xffff0000, v59
	v_pk_add_f32 v[54:55], v[54:55], v[56:57]
	v_pk_add_f32 v[52:53], v[52:53], v[64:65]
	v_pk_add_f32 v[50:51], v[50:51], v[58:59]
	v_pk_add_f32 v[48:49], v[48:49], v[66:67]
	global_store_dwordx4 v[68:69], v[52:55], off offset:512 nt
	global_store_dwordx4 v[68:69], v[48:51], off offset:528 nt
	global_load_dwordx4 v[48:51], v[62:63], off
	v_lshl_add_u64 v[52:53], v[60:61], 2, s[60:61]
	s_waitcnt vmcnt(0)
	v_lshlrev_b32_e32 v54, 16, v48
	v_and_b32_e32 v55, 0xffff0000, v48
	v_lshlrev_b32_e32 v48, 16, v49
	v_and_b32_e32 v49, 0xffff0000, v49
	v_lshlrev_b32_e32 v56, 16, v50
	v_and_b32_e32 v57, 0xffff0000, v50
	v_lshlrev_b32_e32 v50, 16, v51
	v_and_b32_e32 v51, 0xffff0000, v51
	v_pk_add_f32 v[46:47], v[46:47], v[48:49]
	v_pk_add_f32 v[44:45], v[44:45], v[54:55]
	v_pk_add_f32 v[42:43], v[42:43], v[50:51]
	v_pk_add_f32 v[40:41], v[40:41], v[56:57]
	global_store_dwordx4 v[52:53], v[44:47], off nt
	global_store_dwordx4 v[52:53], v[40:43], off offset:16 nt
	global_load_dwordx4 v[40:43], v[62:63], off offset:256
	v_add_u32_e32 v44, 0xa0, v144
	v_ashrrev_i32_e32 v45, 31, v44
	v_lshlrev_b64 v[44:45], 10, v[44:45]
	v_lshl_add_u64 v[44:45], v[44:45], 0, v[142:143]
	v_lshl_add_u64 v[46:47], v[44:45], 1, s[66:67]
	s_waitcnt vmcnt(0)
; #define PG8_BAR __builtin_amdgcn_s_barrier()
;     __device__ __forceinline__ void operator()(const f32x4 (&acc)[2][2][4][2], const Unit& u, int wr, int wc, int fr, int fq) const {
;     ...
;             for (int m = 0; m < 4; ++m) { const int r = u.pm * BM + ai * HALF + wr * 64 + m * 16 + fr; const size_t off = (size_t)r * 1024 + col0;
; #pragma unroll
;                 for (int bj = 0; bj < 2; ++bj) { const u32x4 w = __builtin_nontemporal_load((const u32x4*)(xb + off + bj * HALF));
;                     const f32x4 b0 = {__builtin_bit_cast(float, w.x << 16), __builtin_bit_cast(float, w.x & 0xffff0000u), __builtin_bit_cast(float, w.y << 16), __builtin_bit_cast(float, w.y & 0xffff0000u)};
;                     const f32x4 b1 = {__builtin_bit_cast(float, w.z << 16), __builtin_bit_cast(float, w.z & 0xffff0000u), __builtin_bit_cast(float, w.w << 16), __builtin_bit_cast(float, w.w & 0xffff0000u)};
;                     __builtin_nontemporal_store(b0 + acc[ai][bj][m][0], (f32x4*)(out + off + bj * HALF)); __builtin_nontemporal_store(b1 + acc[ai][bj][m][1], (f32x4*)(out + off + bj * HALF + 4)); } }
; template <class Epi, class Sched, bool ALIGN_EPI = false, bool SP2 = false>
; __device__ __forceinline__ void gemm_phase(PG8_LAS unsigned char* lds, const Gemm g, const Sched& S, const Epi& E) {
;     ...
;         if (!has_next) break;
; #pragma unroll
;         for (int a = 0; a < 2; ++a)
; #pragma unroll
;             for (int b = 0; b < 2; ++b)
; #pragma unroll
;                 for (int m = 0; m < 4; ++m)
; #pragma unroll
;                     for (int n = 0; n < 2; ++n) acc[a][b][m][n] = (f32x4){0.f, 0.f, 0.f, 0.f};
;         cur = nxt; cA = nA; cB = nB; ++ui;
;         if constexpr (ALIGN_EPI) { if (wr == 1) PG8_BAR; }
;     }
	v_lshlrev_b32_e32 v48, 16, v40
	v_and_b32_e32 v49, 0xffff0000, v40
	v_lshlrev_b32_e32 v40, 16, v41
	v_and_b32_e32 v41, 0xffff0000, v41
	v_lshlrev_b32_e32 v50, 16, v42
	v_and_b32_e32 v51, 0xffff0000, v42
	v_lshlrev_b32_e32 v42, 16, v43
	v_and_b32_e32 v43, 0xffff0000, v43
	v_pk_add_f32 v[38:39], v[38:39], v[40:41]
	v_pk_add_f32 v[36:37], v[36:37], v[48:49]
	v_pk_add_f32 v[34:35], v[34:35], v[42:43]
	v_pk_add_f32 v[32:33], v[32:33], v[50:51]
	global_store_dwordx4 v[52:53], v[36:39], off offset:512 nt
	global_store_dwordx4 v[52:53], v[32:35], off offset:528 nt
	global_load_dwordx4 v[32:35], v[46:47], off
	v_lshl_add_u64 v[36:37], v[44:45], 2, s[60:61]
	s_waitcnt vmcnt(0)
	v_lshlrev_b32_e32 v38, 16, v32
	v_and_b32_e32 v39, 0xffff0000, v32
	v_lshlrev_b32_e32 v32, 16, v33
	v_and_b32_e32 v33, 0xffff0000, v33
	v_lshlrev_b32_e32 v40, 16, v34
	v_and_b32_e32 v41, 0xffff0000, v34
	v_lshlrev_b32_e32 v34, 16, v35
	v_and_b32_e32 v35, 0xffff0000, v35
	v_pk_add_f32 v[30:31], v[30:31], v[32:33]
	v_pk_add_f32 v[28:29], v[28:29], v[38:39]
	v_pk_add_f32 v[26:27], v[26:27], v[34:35]
	v_pk_add_f32 v[24:25], v[24:25], v[40:41]
	global_store_dwordx4 v[36:37], v[28:31], off nt
	global_store_dwordx4 v[36:37], v[24:27], off offset:16 nt
	global_load_dwordx4 v[24:27], v[46:47], off offset:256
	v_add_u32_e32 v28, 0xb0, v144
	v_ashrrev_i32_e32 v29, 31, v28
	v_lshlrev_b64 v[28:29], 10, v[28:29]
	v_lshl_add_u64 v[28:29], v[28:29], 0, v[142:143]
	v_lshl_add_u64 v[30:31], v[28:29], 1, s[66:67]
	s_waitcnt vmcnt(0)
	v_lshlrev_b32_e32 v32, 16, v24
	v_and_b32_e32 v33, 0xffff0000, v24
	v_lshlrev_b32_e32 v24, 16, v25
	v_and_b32_e32 v25, 0xffff0000, v25
	v_lshlrev_b32_e32 v34, 16, v26
	v_and_b32_e32 v35, 0xffff0000, v26
	v_lshlrev_b32_e32 v26, 16, v27
	v_and_b32_e32 v27, 0xffff0000, v27
	v_pk_add_f32 v[22:23], v[22:23], v[24:25]
	v_pk_add_f32 v[20:21], v[20:21], v[32:33]
	v_pk_add_f32 v[18:19], v[18:19], v[26:27]
	v_pk_add_f32 v[16:17], v[16:17], v[34:35]
	global_store_dwordx4 v[36:37], v[20:23], off offset:512 nt
	global_store_dwordx4 v[36:37], v[16:19], off offset:528 nt
	global_load_dwordx4 v[16:19], v[30:31], off
	v_lshl_add_u64 v[20:21], v[28:29], 2, s[60:61]
	s_waitcnt vmcnt(0)
	v_lshlrev_b32_e32 v22, 16, v16
	v_and_b32_e32 v23, 0xffff0000, v16
	v_lshlrev_b32_e32 v16, 16, v17
	v_and_b32_e32 v17, 0xffff0000, v17
	v_lshlrev_b32_e32 v24, 16, v18
	v_and_b32_e32 v25, 0xffff0000, v18
	v_lshlrev_b32_e32 v18, 16, v19
	v_and_b32_e32 v19, 0xffff0000, v19
	v_pk_add_f32 v[14:15], v[14:15], v[16:17]
	v_pk_add_f32 v[12:13], v[12:13], v[22:23]
	v_pk_add_f32 v[10:11], v[10:11], v[18:19]
	v_pk_add_f32 v[8:9], v[8:9], v[24:25]
	global_store_dwordx4 v[20:21], v[12:15], off nt
	global_store_dwordx4 v[20:21], v[8:11], off offset:16 nt
	global_load_dwordx4 v[8:11], v[30:31], off offset:256
	s_waitcnt vmcnt(0)
	v_lshlrev_b32_e32 v12, 16, v8
	v_and_b32_e32 v13, 0xffff0000, v8
	v_lshlrev_b32_e32 v8, 16, v9
	v_and_b32_e32 v9, 0xffff0000, v9
	v_lshlrev_b32_e32 v14, 16, v10
	v_and_b32_e32 v15, 0xffff0000, v10
	v_lshlrev_b32_e32 v10, 16, v11
	v_and_b32_e32 v11, 0xffff0000, v11
	v_pk_add_f32 v[6:7], v[6:7], v[8:9]
	v_pk_add_f32 v[4:5], v[4:5], v[12:13]
	v_pk_add_f32 v[2:3], v[2:3], v[10:11]
	v_pk_add_f32 v[0:1], v[0:1], v[14:15]
	global_store_dwordx4 v[20:21], v[4:7], off offset:512 nt
	global_store_dwordx4 v[20:21], v[0:3], off offset:528 nt
	s_cbranch_vccnz .LBB0_1493
	s_andn2_b64 vcc, exec, s[0:1]
	s_cbranch_vccnz .LBB0_1492
	s_barrier
	s_branch .LBB0_1492
